# nt cache policy on the once-read f32 weight loads of the bf16 weight conversion (all four copies)
# speedup vs baseline: 1.0482x; 1.0018x over previous
.LBB0_18:
	s_ashr_i32 s9, s8, 31
	s_lshl_b64 s[8:9], s[8:9], 3
	s_add_u32 s10, s0, s8
	s_addc_u32 s11, s1, s9
	s_lshr_b32 s8, s13, 5
	v_cvt_f32_u32_e32 v10, s8
	s_load_dwordx2 s[28:29], s[10:11], 0x0
	s_sub_i32 s10, 0, s8
	s_abs_i32 s25, s15
	v_rcp_iflag_f32_e32 v10, v10
	s_ashr_i32 s19, s15, 31
	s_mov_b32 s9, 0
	s_mov_b32 s14, 1
	v_mul_f32_e32 v10, 0x4f7ffffe, v10
	v_cvt_u32_f32_e32 v10, v10
	s_nop 0
	v_readfirstlane_b32 s11, v10
	s_mul_i32 s10, s10, s11
	s_mul_hi_u32 s10, s11, s10
	s_add_i32 s11, s11, s10
	s_mul_hi_u32 s10, s25, s11
	s_mul_i32 s11, s10, s8
	s_sub_i32 s11, s25, s11
	s_add_i32 s34, s10, 1
	s_sub_i32 s25, s11, s8
	s_cmp_ge_u32 s11, s8
	s_cselect_b32 s10, s34, s10
	s_cselect_b32 s11, s25, s11
	s_add_i32 s25, s10, 1
	s_cmp_ge_u32 s11, s8
	s_cselect_b32 s10, s25, s10
	s_xor_b32 s10, s10, s19
	s_sub_i32 s10, s10, s19
	s_mul_i32 s8, s10, s8
	s_sub_i32 s11, s15, s8
	s_lshl_b32 s8, s10, 6
	s_lshl_b32 s10, s11, 5
	s_ashr_i32 s11, s10, 31
	s_lshl_b64 s[34:35], s[10:11], 2
	s_waitcnt lgkmcnt(0)
	s_add_u32 s28, s28, s34
	s_addc_u32 s29, s29, s35
	s_mul_i32 s70, s8, s13
	s_lshl_b32 s71, s13, 2
	s_lshl_b32 s70, s70, 2
	s_add_u32 s28, s28, s70
	s_addc_u32 s29, s29, 0
	v_mad_u32_u24 v210, v2, s71, v4
	v_mad_u32_u24 v211, v2, s3, v6
	s_lshl_b32 s71, s71, 1
	global_load_dword v166, v210, s[28:29] nt
	s_add_u32 s28, s28, s71
	s_addc_u32 s29, s29, 0
	global_load_dword v167, v210, s[28:29] nt
	s_add_u32 s28, s28, s71
	s_addc_u32 s29, s29, 0
	global_load_dword v168, v210, s[28:29] nt
	s_add_u32 s28, s28, s71
	s_addc_u32 s29, s29, 0
	global_load_dword v169, v210, s[28:29] nt
	s_add_u32 s28, s28, s71
	s_addc_u32 s29, s29, 0
	global_load_dword v170, v210, s[28:29] nt
	s_add_u32 s28, s28, s71
	s_addc_u32 s29, s29, 0
	global_load_dword v171, v210, s[28:29] nt
	s_add_u32 s28, s28, s71
	s_addc_u32 s29, s29, 0
	global_load_dword v172, v210, s[28:29] nt
	s_add_u32 s28, s28, s71
	s_addc_u32 s29, s29, 0
	global_load_dword v173, v210, s[28:29] nt
	s_add_u32 s28, s28, s71
	s_addc_u32 s29, s29, 0
	global_load_dword v174, v210, s[28:29] nt
	s_add_u32 s28, s28, s71
	s_addc_u32 s29, s29, 0
	global_load_dword v175, v210, s[28:29] nt
	s_add_u32 s28, s28, s71
	s_addc_u32 s29, s29, 0
	global_load_dword v176, v210, s[28:29] nt
	s_add_u32 s28, s28, s71
	s_addc_u32 s29, s29, 0
	global_load_dword v177, v210, s[28:29] nt
	s_add_u32 s28, s28, s71
	s_addc_u32 s29, s29, 0
	global_load_dword v178, v210, s[28:29] nt
	s_add_u32 s28, s28, s71
	s_addc_u32 s29, s29, 0
	global_load_dword v179, v210, s[28:29] nt
	s_add_u32 s28, s28, s71
	s_addc_u32 s29, s29, 0
	global_load_dword v180, v210, s[28:29] nt
	s_add_u32 s28, s28, s71
	s_addc_u32 s29, s29, 0
	global_load_dword v181, v210, s[28:29] nt
	s_add_u32 s28, s28, s71
	s_addc_u32 s29, s29, 0
	global_load_dword v182, v210, s[28:29] nt
	s_add_u32 s28, s28, s71
	s_addc_u32 s29, s29, 0
	global_load_dword v183, v210, s[28:29] nt
	s_add_u32 s28, s28, s71
	s_addc_u32 s29, s29, 0
	global_load_dword v184, v210, s[28:29] nt
	s_add_u32 s28, s28, s71
	s_addc_u32 s29, s29, 0
	global_load_dword v185, v210, s[28:29] nt
	s_add_u32 s28, s28, s71
	s_addc_u32 s29, s29, 0
	global_load_dword v186, v210, s[28:29] nt
	s_add_u32 s28, s28, s71
	s_addc_u32 s29, s29, 0
	global_load_dword v187, v210, s[28:29] nt
	s_add_u32 s28, s28, s71
	s_addc_u32 s29, s29, 0
	global_load_dword v188, v210, s[28:29] nt
	s_add_u32 s28, s28, s71
	s_addc_u32 s29, s29, 0
	global_load_dword v189, v210, s[28:29] nt
	s_add_u32 s28, s28, s71
	s_addc_u32 s29, s29, 0
	global_load_dword v190, v210, s[28:29] nt
	s_add_u32 s28, s28, s71
	s_addc_u32 s29, s29, 0
	global_load_dword v191, v210, s[28:29] nt
	s_add_u32 s28, s28, s71
	s_addc_u32 s29, s29, 0
	global_load_dword v192, v210, s[28:29] nt
	s_add_u32 s28, s28, s71
	s_addc_u32 s29, s29, 0
	global_load_dword v193, v210, s[28:29] nt
	s_add_u32 s28, s28, s71
	s_addc_u32 s29, s29, 0
	global_load_dword v194, v210, s[28:29] nt
	s_add_u32 s28, s28, s71
	s_addc_u32 s29, s29, 0
	global_load_dword v195, v210, s[28:29] nt
	s_add_u32 s28, s28, s71
	s_addc_u32 s29, s29, 0
	global_load_dword v198, v210, s[28:29] nt
	s_add_u32 s28, s28, s71
	s_addc_u32 s29, s29, 0
	global_load_dword v199, v210, s[28:29] nt
	s_waitcnt vmcnt(31)
	ds_write_b32 v211, v166
	s_waitcnt vmcnt(30)
	ds_write_b32 v211, v167 offset:264
	s_waitcnt vmcnt(29)
	ds_write_b32 v211, v168 offset:528
	s_waitcnt vmcnt(28)
	ds_write_b32 v211, v169 offset:792
	s_waitcnt vmcnt(27)
	ds_write_b32 v211, v170 offset:1056
	s_waitcnt vmcnt(26)
	ds_write_b32 v211, v171 offset:1320
	s_waitcnt vmcnt(25)
	ds_write_b32 v211, v172 offset:1584
	s_waitcnt vmcnt(24)
	ds_write_b32 v211, v173 offset:1848
	s_waitcnt vmcnt(23)
	ds_write_b32 v211, v174 offset:2112
	s_waitcnt vmcnt(22)
	ds_write_b32 v211, v175 offset:2376
	s_waitcnt vmcnt(21)
	ds_write_b32 v211, v176 offset:2640
	s_waitcnt vmcnt(20)
	ds_write_b32 v211, v177 offset:2904
	s_waitcnt vmcnt(19)
	ds_write_b32 v211, v178 offset:3168
	s_waitcnt vmcnt(18)
	ds_write_b32 v211, v179 offset:3432
	s_waitcnt vmcnt(17)
	ds_write_b32 v211, v180 offset:3696
	s_waitcnt vmcnt(16)
	ds_write_b32 v211, v181 offset:3960
	s_waitcnt vmcnt(15)
	ds_write_b32 v211, v182 offset:4224
	s_waitcnt vmcnt(14)
	ds_write_b32 v211, v183 offset:4488
	s_waitcnt vmcnt(13)
	ds_write_b32 v211, v184 offset:4752
	s_waitcnt vmcnt(12)
	ds_write_b32 v211, v185 offset:5016
	s_waitcnt vmcnt(11)
	ds_write_b32 v211, v186 offset:5280
	s_waitcnt vmcnt(10)
	ds_write_b32 v211, v187 offset:5544
	s_waitcnt vmcnt(9)
	ds_write_b32 v211, v188 offset:5808
	s_waitcnt vmcnt(8)
	ds_write_b32 v211, v189 offset:6072
	s_waitcnt vmcnt(7)
	ds_write_b32 v211, v190 offset:6336
	s_waitcnt vmcnt(6)
	ds_write_b32 v211, v191 offset:6600
	s_waitcnt vmcnt(5)
	ds_write_b32 v211, v192 offset:6864
	s_waitcnt vmcnt(4)
	ds_write_b32 v211, v193 offset:7128
	s_waitcnt vmcnt(3)
	ds_write_b32 v211, v194 offset:7392
	s_waitcnt vmcnt(2)
	ds_write_b32 v211, v195 offset:7656
	s_waitcnt vmcnt(1)
	ds_write_b32 v211, v198 offset:7920
	s_waitcnt vmcnt(0)
	ds_write_b32 v211, v199 offset:8184
	s_waitcnt lgkmcnt(0)
	s_add_i32 s10, s10, s12
	v_add_u32_e32 v22, s10, v3
	ds_read2_b32 v[166:167], v7 offset1:33
	ds_read2_b32 v[168:169], v7 offset0:66 offset1:99
	ds_read2_b32 v[170:171], v7 offset0:132 offset1:165
	ds_read2_b32 v[172:173], v7 offset0:198 offset1:231
	ds_read2_b32 v[174:175], v7 offset0:8 offset1:41
	ds_read2_b32 v[176:177], v7 offset0:74 offset1:107
	ds_read2_b32 v[178:179], v7 offset0:140 offset1:173
	ds_read2_b32 v[180:181], v7 offset0:206 offset1:239
	ds_read2_b32 v[182:183], v7 offset0:16 offset1:49
	ds_read2_b32 v[184:185], v7 offset0:82 offset1:115
	ds_read2_b32 v[186:187], v7 offset0:148 offset1:181
	ds_read2_b32 v[188:189], v7 offset0:214 offset1:247
	ds_read2_b32 v[190:191], v7 offset0:24 offset1:57
	ds_read2_b32 v[192:193], v7 offset0:90 offset1:123
	ds_read2_b32 v[194:195], v7 offset0:156 offset1:189
	ds_read2_b32 v[198:199], v7 offset0:222 offset1:255
	s_ashr_i32 s9, s8, 31
	v_ashrrev_i32_e32 v23, 31, v22
	s_waitcnt lgkmcnt(12)
	v_cvt_pk_bf16_f32 v16, v166, v167
	v_lshl_add_u64 v[20:21], s[8:9], 1, v[8:9]
	v_lshlrev_b64 v[22:23], 12, v[22:23]
	s_waitcnt lgkmcnt(12)
	v_cvt_pk_bf16_f32 v17, v168, v169
	v_lshl_add_u64 v[22:23], v[20:21], 0, v[22:23]
	s_waitcnt lgkmcnt(12)
	v_cvt_pk_bf16_f32 v18, v170, v171
	s_waitcnt lgkmcnt(12)
	v_cvt_pk_bf16_f32 v19, v172, v173
	global_store_dwordx4 v[22:23], v[16:19], off
	s_nop 1
	v_add_u32_e32 v22, s10, v12
	v_ashrrev_i32_e32 v23, 31, v22
	s_waitcnt lgkmcnt(8)
	v_cvt_pk_bf16_f32 v16, v174, v175
	v_lshlrev_b64 v[22:23], 12, v[22:23]
	s_waitcnt lgkmcnt(8)
	v_cvt_pk_bf16_f32 v17, v176, v177
	v_lshl_add_u64 v[22:23], v[20:21], 0, v[22:23]
	s_waitcnt lgkmcnt(8)
	v_cvt_pk_bf16_f32 v18, v178, v179
	s_waitcnt lgkmcnt(8)
	v_cvt_pk_bf16_f32 v19, v180, v181
	global_store_dwordx4 v[22:23], v[16:19], off
	s_nop 1
	v_add_u32_e32 v22, s10, v13
	v_ashrrev_i32_e32 v23, 31, v22
	s_waitcnt lgkmcnt(4)
	v_cvt_pk_bf16_f32 v16, v182, v183
	v_lshlrev_b64 v[22:23], 12, v[22:23]
	s_waitcnt lgkmcnt(4)
	v_cvt_pk_bf16_f32 v17, v184, v185
	v_lshl_add_u64 v[22:23], v[20:21], 0, v[22:23]
	s_waitcnt lgkmcnt(4)
	v_cvt_pk_bf16_f32 v18, v186, v187
	s_waitcnt lgkmcnt(4)
	v_cvt_pk_bf16_f32 v19, v188, v189
	global_store_dwordx4 v[22:23], v[16:19], off
	s_nop 1
	v_add_u32_e32 v22, s10, v14
	v_ashrrev_i32_e32 v23, 31, v22
	s_waitcnt lgkmcnt(0)
	v_cvt_pk_bf16_f32 v16, v190, v191
	v_lshlrev_b64 v[22:23], 12, v[22:23]
	s_waitcnt lgkmcnt(0)
	v_cvt_pk_bf16_f32 v17, v192, v193
	v_lshl_add_u64 v[20:21], v[20:21], 0, v[22:23]
	s_waitcnt lgkmcnt(0)
	v_cvt_pk_bf16_f32 v18, v194, v195
	s_waitcnt lgkmcnt(0)
	v_cvt_pk_bf16_f32 v19, v198, v199
	global_store_dwordx4 v[20:21], v[16:19], off
	s_nop 1
	s_waitcnt lgkmcnt(0)
	s_add_i32 s5, s5, s18
	s_cmpk_gt_i32 s5, 0x33ff
	s_cbranch_scc0 .LBB0_7
	s_branch .LBB0_22

.LBB0_271:
	s_ashr_i32 s9, s8, 31
	s_lshl_b64 s[8:9], s[8:9], 3
	s_add_u32 s10, s0, s8
	s_addc_u32 s11, s1, s9
	s_lshr_b32 s8, s38, 5
	v_cvt_f32_u32_e32 v8, s8
	s_load_dwordx2 s[40:41], s[10:11], 0x0
	s_sub_i32 s10, 0, s8
	s_abs_i32 s13, s29
	v_rcp_iflag_f32_e32 v8, v8
	s_ashr_i32 s12, s29, 31
	s_mov_b32 s9, 0
	s_mov_b32 s39, 1
	v_mul_f32_e32 v8, 0x4f7ffffe, v8
	v_cvt_u32_f32_e32 v8, v8
	s_nop 0
	v_readfirstlane_b32 s11, v8
	s_mul_i32 s10, s10, s11
	s_mul_hi_u32 s10, s11, s10
	s_add_i32 s11, s11, s10
	s_mul_hi_u32 s10, s13, s11
	s_mul_i32 s11, s10, s8
	s_sub_i32 s11, s13, s11
	s_add_i32 s42, s10, 1
	s_sub_i32 s13, s11, s8
	s_cmp_ge_u32 s11, s8
	s_cselect_b32 s10, s42, s10
	s_cselect_b32 s11, s13, s11
	s_add_i32 s13, s10, 1
	s_cmp_ge_u32 s11, s8
	s_cselect_b32 s10, s13, s10
	s_xor_b32 s10, s10, s12
	s_sub_i32 s10, s10, s12
	s_mul_i32 s8, s10, s8
	s_sub_i32 s11, s29, s8
	s_lshl_b32 s8, s10, 6
	s_lshl_b32 s10, s11, 5
	s_ashr_i32 s11, s10, 31
	s_lshl_b64 s[42:43], s[10:11], 2
	s_waitcnt lgkmcnt(0)
	s_add_u32 s40, s40, s42
	s_addc_u32 s41, s41, s43
	s_mul_i32 s70, s8, s38
	s_lshl_b32 s71, s38, 2
	s_lshl_b32 s70, s70, 2
	s_add_u32 s40, s40, s70
	s_addc_u32 s41, s41, 0
	v_mad_u32_u24 v210, v0, s71, v2
	v_mad_u32_u24 v211, v0, s15, v4
	s_lshl_b32 s71, s71, 1
	global_load_dword v166, v210, s[40:41] nt
	s_add_u32 s40, s40, s71
	s_addc_u32 s41, s41, 0
	global_load_dword v167, v210, s[40:41] nt
	s_add_u32 s40, s40, s71
	s_addc_u32 s41, s41, 0
	global_load_dword v168, v210, s[40:41] nt
	s_add_u32 s40, s40, s71
	s_addc_u32 s41, s41, 0
	global_load_dword v169, v210, s[40:41] nt
	s_add_u32 s40, s40, s71
	s_addc_u32 s41, s41, 0
	global_load_dword v170, v210, s[40:41] nt
	s_add_u32 s40, s40, s71
	s_addc_u32 s41, s41, 0
	global_load_dword v171, v210, s[40:41] nt
	s_add_u32 s40, s40, s71
	s_addc_u32 s41, s41, 0
	global_load_dword v172, v210, s[40:41] nt
	s_add_u32 s40, s40, s71
	s_addc_u32 s41, s41, 0
	global_load_dword v173, v210, s[40:41] nt
	s_add_u32 s40, s40, s71
	s_addc_u32 s41, s41, 0
	global_load_dword v174, v210, s[40:41] nt
	s_add_u32 s40, s40, s71
	s_addc_u32 s41, s41, 0
	global_load_dword v175, v210, s[40:41] nt
	s_add_u32 s40, s40, s71
	s_addc_u32 s41, s41, 0
	global_load_dword v176, v210, s[40:41] nt
	s_add_u32 s40, s40, s71
	s_addc_u32 s41, s41, 0
	global_load_dword v177, v210, s[40:41] nt
	s_add_u32 s40, s40, s71
	s_addc_u32 s41, s41, 0
	global_load_dword v178, v210, s[40:41] nt
	s_add_u32 s40, s40, s71
	s_addc_u32 s41, s41, 0
	global_load_dword v179, v210, s[40:41] nt
	s_add_u32 s40, s40, s71
	s_addc_u32 s41, s41, 0
	global_load_dword v180, v210, s[40:41] nt
	s_add_u32 s40, s40, s71
	s_addc_u32 s41, s41, 0
	global_load_dword v181, v210, s[40:41] nt
	s_add_u32 s40, s40, s71
	s_addc_u32 s41, s41, 0
	global_load_dword v182, v210, s[40:41] nt
	s_add_u32 s40, s40, s71
	s_addc_u32 s41, s41, 0
	global_load_dword v183, v210, s[40:41] nt
	s_add_u32 s40, s40, s71
	s_addc_u32 s41, s41, 0
	global_load_dword v184, v210, s[40:41] nt
	s_add_u32 s40, s40, s71
	s_addc_u32 s41, s41, 0
	global_load_dword v185, v210, s[40:41] nt
	s_add_u32 s40, s40, s71
	s_addc_u32 s41, s41, 0
	global_load_dword v186, v210, s[40:41] nt
	s_add_u32 s40, s40, s71
	s_addc_u32 s41, s41, 0
	global_load_dword v187, v210, s[40:41] nt
	s_add_u32 s40, s40, s71
	s_addc_u32 s41, s41, 0
	global_load_dword v188, v210, s[40:41] nt
	s_add_u32 s40, s40, s71
	s_addc_u32 s41, s41, 0
	global_load_dword v189, v210, s[40:41] nt
	s_add_u32 s40, s40, s71
	s_addc_u32 s41, s41, 0
	global_load_dword v190, v210, s[40:41] nt
	s_add_u32 s40, s40, s71
	s_addc_u32 s41, s41, 0
	global_load_dword v191, v210, s[40:41] nt
	s_add_u32 s40, s40, s71
	s_addc_u32 s41, s41, 0
	global_load_dword v192, v210, s[40:41] nt
	s_add_u32 s40, s40, s71
	s_addc_u32 s41, s41, 0
	global_load_dword v193, v210, s[40:41] nt
	s_add_u32 s40, s40, s71
	s_addc_u32 s41, s41, 0
	global_load_dword v194, v210, s[40:41] nt
	s_add_u32 s40, s40, s71
	s_addc_u32 s41, s41, 0
	global_load_dword v195, v210, s[40:41] nt
	s_add_u32 s40, s40, s71
	s_addc_u32 s41, s41, 0
	global_load_dword v198, v210, s[40:41] nt
	s_add_u32 s40, s40, s71
	s_addc_u32 s41, s41, 0
	global_load_dword v199, v210, s[40:41] nt
	s_waitcnt vmcnt(31)
	ds_write_b32 v211, v166
	s_waitcnt vmcnt(30)
	ds_write_b32 v211, v167 offset:264
	s_waitcnt vmcnt(29)
	ds_write_b32 v211, v168 offset:528
	s_waitcnt vmcnt(28)
	ds_write_b32 v211, v169 offset:792
	s_waitcnt vmcnt(27)
	ds_write_b32 v211, v170 offset:1056
	s_waitcnt vmcnt(26)
	ds_write_b32 v211, v171 offset:1320
	s_waitcnt vmcnt(25)
	ds_write_b32 v211, v172 offset:1584
	s_waitcnt vmcnt(24)
	ds_write_b32 v211, v173 offset:1848
	s_waitcnt vmcnt(23)
	ds_write_b32 v211, v174 offset:2112
	s_waitcnt vmcnt(22)
	ds_write_b32 v211, v175 offset:2376
	s_waitcnt vmcnt(21)
	ds_write_b32 v211, v176 offset:2640
	s_waitcnt vmcnt(20)
	ds_write_b32 v211, v177 offset:2904
	s_waitcnt vmcnt(19)
	ds_write_b32 v211, v178 offset:3168
	s_waitcnt vmcnt(18)
	ds_write_b32 v211, v179 offset:3432
	s_waitcnt vmcnt(17)
	ds_write_b32 v211, v180 offset:3696
	s_waitcnt vmcnt(16)
	ds_write_b32 v211, v181 offset:3960
	s_waitcnt vmcnt(15)
	ds_write_b32 v211, v182 offset:4224
	s_waitcnt vmcnt(14)
	ds_write_b32 v211, v183 offset:4488
	s_waitcnt vmcnt(13)
	ds_write_b32 v211, v184 offset:4752
	s_waitcnt vmcnt(12)
	ds_write_b32 v211, v185 offset:5016
	s_waitcnt vmcnt(11)
	ds_write_b32 v211, v186 offset:5280
	s_waitcnt vmcnt(10)
	ds_write_b32 v211, v187 offset:5544
	s_waitcnt vmcnt(9)
	ds_write_b32 v211, v188 offset:5808
	s_waitcnt vmcnt(8)
	ds_write_b32 v211, v189 offset:6072
	s_waitcnt vmcnt(7)
	ds_write_b32 v211, v190 offset:6336
	s_waitcnt vmcnt(6)
	ds_write_b32 v211, v191 offset:6600
	s_waitcnt vmcnt(5)
	ds_write_b32 v211, v192 offset:6864
	s_waitcnt vmcnt(4)
	ds_write_b32 v211, v193 offset:7128
	s_waitcnt vmcnt(3)
	ds_write_b32 v211, v194 offset:7392
	s_waitcnt vmcnt(2)
	ds_write_b32 v211, v195 offset:7656
	s_waitcnt vmcnt(1)
	ds_write_b32 v211, v198 offset:7920
	s_waitcnt vmcnt(0)
	ds_write_b32 v211, v199 offset:8184
	s_add_u32 s6, s34, s6
	s_waitcnt lgkmcnt(0)
	s_addc_u32 s7, s35, s7
	s_add_i32 s10, s10, s25
	s_lshl_b64 s[4:5], s[4:5], 1
	s_add_u32 s6, s6, s4
	ds_read2_b32 v[166:167], v10 offset1:33
	ds_read2_b32 v[168:169], v10 offset0:66 offset1:99
	ds_read2_b32 v[170:171], v10 offset0:132 offset1:165
	ds_read2_b32 v[172:173], v10 offset0:198 offset1:231
	ds_read2_b32 v[174:175], v10 offset0:8 offset1:41
	ds_read2_b32 v[176:177], v10 offset0:74 offset1:107
	ds_read2_b32 v[178:179], v10 offset0:140 offset1:173
	ds_read2_b32 v[180:181], v10 offset0:206 offset1:239
	ds_read2_b32 v[182:183], v10 offset0:16 offset1:49
	ds_read2_b32 v[184:185], v10 offset0:82 offset1:115
	ds_read2_b32 v[186:187], v10 offset0:148 offset1:181
	ds_read2_b32 v[188:189], v10 offset0:214 offset1:247
	ds_read2_b32 v[190:191], v10 offset0:24 offset1:57
	ds_read2_b32 v[192:193], v10 offset0:90 offset1:123
	ds_read2_b32 v[194:195], v10 offset0:156 offset1:189
	ds_read2_b32 v[198:199], v10 offset0:222 offset1:255
	s_addc_u32 s7, s7, s5
	s_ashr_i32 s9, s8, 31
	s_waitcnt lgkmcnt(12)
	v_cvt_pk_bf16_f32 v14, v166, v167
	s_lshl_b64 s[4:5], s[8:9], 1
	s_waitcnt lgkmcnt(12)
	v_cvt_pk_bf16_f32 v15, v168, v169
	v_add_u32_e32 v18, s10, v5
	s_add_u32 s4, s6, s4
	v_ashrrev_i32_e32 v19, 31, v18
	s_waitcnt lgkmcnt(12)
	v_cvt_pk_bf16_f32 v16, v170, v171
	s_addc_u32 s5, s7, s5
	v_lshl_add_u64 v[20:21], s[4:5], 0, v[6:7]
	s_waitcnt lgkmcnt(12)
	v_cvt_pk_bf16_f32 v17, v172, v173
	v_lshlrev_b64 v[8:9], 12, v[18:19]
	v_lshl_add_u64 v[8:9], v[20:21], 0, v[8:9]
	global_store_dwordx4 v[8:9], v[14:17], off
	s_nop 1
	v_add_u32_e32 v18, s10, v11
	v_ashrrev_i32_e32 v19, 31, v18
	s_waitcnt lgkmcnt(8)
	v_cvt_pk_bf16_f32 v14, v174, v175
	v_lshlrev_b64 v[18:19], 12, v[18:19]
	s_waitcnt lgkmcnt(8)
	v_cvt_pk_bf16_f32 v15, v176, v177
	v_lshl_add_u64 v[18:19], v[20:21], 0, v[18:19]
	s_waitcnt lgkmcnt(8)
	v_cvt_pk_bf16_f32 v16, v178, v179
	s_waitcnt lgkmcnt(8)
	v_cvt_pk_bf16_f32 v17, v180, v181
	global_store_dwordx4 v[18:19], v[14:17], off
	s_nop 1
	v_add_u32_e32 v18, s10, v12
	v_ashrrev_i32_e32 v19, 31, v18
	s_waitcnt lgkmcnt(4)
	v_cvt_pk_bf16_f32 v14, v182, v183
	v_lshlrev_b64 v[18:19], 12, v[18:19]
	s_waitcnt lgkmcnt(4)
	v_cvt_pk_bf16_f32 v15, v184, v185
	v_lshl_add_u64 v[18:19], v[20:21], 0, v[18:19]
	s_waitcnt lgkmcnt(4)
	v_cvt_pk_bf16_f32 v16, v186, v187
	s_waitcnt lgkmcnt(4)
	v_cvt_pk_bf16_f32 v17, v188, v189
	global_store_dwordx4 v[18:19], v[14:17], off
	s_nop 1
	v_add_u32_e32 v18, s10, v13
	v_ashrrev_i32_e32 v19, 31, v18
	s_waitcnt lgkmcnt(0)
	v_cvt_pk_bf16_f32 v14, v190, v191
	v_lshlrev_b64 v[18:19], 12, v[18:19]
	s_waitcnt lgkmcnt(0)
	v_cvt_pk_bf16_f32 v15, v192, v193
	v_lshl_add_u64 v[18:19], v[20:21], 0, v[18:19]
	s_waitcnt lgkmcnt(0)
	v_cvt_pk_bf16_f32 v16, v194, v195
	s_waitcnt lgkmcnt(0)
	v_cvt_pk_bf16_f32 v17, v198, v199
	global_store_dwordx4 v[18:19], v[14:17], off
	s_nop 1
	s_waitcnt lgkmcnt(0)
	s_add_i32 s3, s3, s14
	s_cmpk_lt_i32 s3, 0x5400
	s_cbranch_scc1 .LBB0_240
	s_branch .LBB0_275

.LBB0_490:
	s_ashr_i32 s9, s8, 31
	s_lshl_b64 s[8:9], s[8:9], 3
	s_add_u32 s10, s0, s8
	s_addc_u32 s11, s1, s9
	s_lshr_b32 s8, s19, 5
	v_cvt_f32_u32_e32 v8, s8
	s_load_dwordx2 s[40:41], s[10:11], 0x0
	s_sub_i32 s10, 0, s8
	s_abs_i32 s13, s29
	v_rcp_iflag_f32_e32 v8, v8
	s_ashr_i32 s12, s29, 31
	s_mov_b32 s9, 0
	s_mov_b32 s38, 1
	v_mul_f32_e32 v8, 0x4f7ffffe, v8
	v_cvt_u32_f32_e32 v8, v8
	s_nop 0
	v_readfirstlane_b32 s11, v8
	s_mul_i32 s10, s10, s11
	s_mul_hi_u32 s10, s11, s10
	s_add_i32 s11, s11, s10
	s_mul_hi_u32 s10, s13, s11
	s_mul_i32 s11, s10, s8
	s_sub_i32 s11, s13, s11
	s_add_i32 s39, s10, 1
	s_sub_i32 s13, s11, s8
	s_cmp_ge_u32 s11, s8
	s_cselect_b32 s10, s39, s10
	s_cselect_b32 s11, s13, s11
	s_add_i32 s13, s10, 1
	s_cmp_ge_u32 s11, s8
	s_cselect_b32 s10, s13, s10
	s_xor_b32 s10, s10, s12
	s_sub_i32 s10, s10, s12
	s_mul_i32 s8, s10, s8
	s_sub_i32 s11, s29, s8
	s_lshl_b32 s8, s10, 6
	s_lshl_b32 s10, s11, 5
	s_ashr_i32 s11, s10, 31
	s_lshl_b64 s[42:43], s[10:11], 2
	s_waitcnt lgkmcnt(0)
	s_add_u32 s40, s40, s42
	s_addc_u32 s41, s41, s43
	s_mul_i32 s70, s8, s19
	s_lshl_b32 s71, s19, 2
	s_lshl_b32 s70, s70, 2
	s_add_u32 s40, s40, s70
	s_addc_u32 s41, s41, 0
	v_mad_u32_u24 v210, v0, s71, v6
	v_mad_u32_u24 v211, v0, s15, v4
	s_lshl_b32 s71, s71, 1
	global_load_dword v166, v210, s[40:41] nt
	s_add_u32 s40, s40, s71
	s_addc_u32 s41, s41, 0
	global_load_dword v167, v210, s[40:41] nt
	s_add_u32 s40, s40, s71
	s_addc_u32 s41, s41, 0
	global_load_dword v168, v210, s[40:41] nt
	s_add_u32 s40, s40, s71
	s_addc_u32 s41, s41, 0
	global_load_dword v169, v210, s[40:41] nt
	s_add_u32 s40, s40, s71
	s_addc_u32 s41, s41, 0
	global_load_dword v170, v210, s[40:41] nt
	s_add_u32 s40, s40, s71
	s_addc_u32 s41, s41, 0
	global_load_dword v171, v210, s[40:41] nt
	s_add_u32 s40, s40, s71
	s_addc_u32 s41, s41, 0
	global_load_dword v172, v210, s[40:41] nt
	s_add_u32 s40, s40, s71
	s_addc_u32 s41, s41, 0
	global_load_dword v173, v210, s[40:41] nt
	s_add_u32 s40, s40, s71
	s_addc_u32 s41, s41, 0
	global_load_dword v174, v210, s[40:41] nt
	s_add_u32 s40, s40, s71
	s_addc_u32 s41, s41, 0
	global_load_dword v175, v210, s[40:41] nt
	s_add_u32 s40, s40, s71
	s_addc_u32 s41, s41, 0
	global_load_dword v176, v210, s[40:41] nt
	s_add_u32 s40, s40, s71
	s_addc_u32 s41, s41, 0
	global_load_dword v177, v210, s[40:41] nt
	s_add_u32 s40, s40, s71
	s_addc_u32 s41, s41, 0
	global_load_dword v178, v210, s[40:41] nt
	s_add_u32 s40, s40, s71
	s_addc_u32 s41, s41, 0
	global_load_dword v179, v210, s[40:41] nt
	s_add_u32 s40, s40, s71
	s_addc_u32 s41, s41, 0
	global_load_dword v180, v210, s[40:41] nt
	s_add_u32 s40, s40, s71
	s_addc_u32 s41, s41, 0
	global_load_dword v181, v210, s[40:41] nt
	s_add_u32 s40, s40, s71
	s_addc_u32 s41, s41, 0
	global_load_dword v182, v210, s[40:41] nt
	s_add_u32 s40, s40, s71
	s_addc_u32 s41, s41, 0
	global_load_dword v183, v210, s[40:41] nt
	s_add_u32 s40, s40, s71
	s_addc_u32 s41, s41, 0
	global_load_dword v184, v210, s[40:41] nt
	s_add_u32 s40, s40, s71
	s_addc_u32 s41, s41, 0
	global_load_dword v185, v210, s[40:41] nt
	s_add_u32 s40, s40, s71
	s_addc_u32 s41, s41, 0
	global_load_dword v186, v210, s[40:41] nt
	s_add_u32 s40, s40, s71
	s_addc_u32 s41, s41, 0
	global_load_dword v187, v210, s[40:41] nt
	s_add_u32 s40, s40, s71
	s_addc_u32 s41, s41, 0
	global_load_dword v188, v210, s[40:41] nt
	s_add_u32 s40, s40, s71
	s_addc_u32 s41, s41, 0
	global_load_dword v189, v210, s[40:41] nt
	s_add_u32 s40, s40, s71
	s_addc_u32 s41, s41, 0
	global_load_dword v190, v210, s[40:41] nt
	s_add_u32 s40, s40, s71
	s_addc_u32 s41, s41, 0
	global_load_dword v191, v210, s[40:41] nt
	s_add_u32 s40, s40, s71
	s_addc_u32 s41, s41, 0
	global_load_dword v192, v210, s[40:41] nt
	s_add_u32 s40, s40, s71
	s_addc_u32 s41, s41, 0
	global_load_dword v193, v210, s[40:41] nt
	s_add_u32 s40, s40, s71
	s_addc_u32 s41, s41, 0
	global_load_dword v194, v210, s[40:41] nt
	s_add_u32 s40, s40, s71
	s_addc_u32 s41, s41, 0
	global_load_dword v195, v210, s[40:41] nt
	s_add_u32 s40, s40, s71
	s_addc_u32 s41, s41, 0
	global_load_dword v198, v210, s[40:41] nt
	s_add_u32 s40, s40, s71
	s_addc_u32 s41, s41, 0
	global_load_dword v199, v210, s[40:41] nt
	s_waitcnt vmcnt(31)
	ds_write_b32 v211, v166
	s_waitcnt vmcnt(30)
	ds_write_b32 v211, v167 offset:264
	s_waitcnt vmcnt(29)
	ds_write_b32 v211, v168 offset:528
	s_waitcnt vmcnt(28)
	ds_write_b32 v211, v169 offset:792
	s_waitcnt vmcnt(27)
	ds_write_b32 v211, v170 offset:1056
	s_waitcnt vmcnt(26)
	ds_write_b32 v211, v171 offset:1320
	s_waitcnt vmcnt(25)
	ds_write_b32 v211, v172 offset:1584
	s_waitcnt vmcnt(24)
	ds_write_b32 v211, v173 offset:1848
	s_waitcnt vmcnt(23)
	ds_write_b32 v211, v174 offset:2112
	s_waitcnt vmcnt(22)
	ds_write_b32 v211, v175 offset:2376
	s_waitcnt vmcnt(21)
	ds_write_b32 v211, v176 offset:2640
	s_waitcnt vmcnt(20)
	ds_write_b32 v211, v177 offset:2904
	s_waitcnt vmcnt(19)
	ds_write_b32 v211, v178 offset:3168
	s_waitcnt vmcnt(18)
	ds_write_b32 v211, v179 offset:3432
	s_waitcnt vmcnt(17)
	ds_write_b32 v211, v180 offset:3696
	s_waitcnt vmcnt(16)
	ds_write_b32 v211, v181 offset:3960
	s_waitcnt vmcnt(15)
	ds_write_b32 v211, v182 offset:4224
	s_waitcnt vmcnt(14)
	ds_write_b32 v211, v183 offset:4488
	s_waitcnt vmcnt(13)
	ds_write_b32 v211, v184 offset:4752
	s_waitcnt vmcnt(12)
	ds_write_b32 v211, v185 offset:5016
	s_waitcnt vmcnt(11)
	ds_write_b32 v211, v186 offset:5280
	s_waitcnt vmcnt(10)
	ds_write_b32 v211, v187 offset:5544
	s_waitcnt vmcnt(9)
	ds_write_b32 v211, v188 offset:5808
	s_waitcnt vmcnt(8)
	ds_write_b32 v211, v189 offset:6072
	s_waitcnt vmcnt(7)
	ds_write_b32 v211, v190 offset:6336
	s_waitcnt vmcnt(6)
	ds_write_b32 v211, v191 offset:6600
	s_waitcnt vmcnt(5)
	ds_write_b32 v211, v192 offset:6864
	s_waitcnt vmcnt(4)
	ds_write_b32 v211, v193 offset:7128
	s_waitcnt vmcnt(3)
	ds_write_b32 v211, v194 offset:7392
	s_waitcnt vmcnt(2)
	ds_write_b32 v211, v195 offset:7656
	s_waitcnt vmcnt(1)
	ds_write_b32 v211, v198 offset:7920
	s_waitcnt vmcnt(0)
	ds_write_b32 v211, v199 offset:8184
	s_add_u32 s9, s34, s4
	s_waitcnt lgkmcnt(0)
	s_addc_u32 s11, s35, s5
	s_add_i32 s10, s10, s25
	s_lshl_b64 s[4:5], s[6:7], 1
	s_add_u32 s6, s9, s4
	ds_read2_b32 v[166:167], v10 offset1:33
	ds_read2_b32 v[168:169], v10 offset0:66 offset1:99
	ds_read2_b32 v[170:171], v10 offset0:132 offset1:165
	ds_read2_b32 v[172:173], v10 offset0:198 offset1:231
	ds_read2_b32 v[174:175], v10 offset0:8 offset1:41
	ds_read2_b32 v[176:177], v10 offset0:74 offset1:107
	ds_read2_b32 v[178:179], v10 offset0:140 offset1:173
	ds_read2_b32 v[180:181], v10 offset0:206 offset1:239
	ds_read2_b32 v[182:183], v10 offset0:16 offset1:49
	ds_read2_b32 v[184:185], v10 offset0:82 offset1:115
	ds_read2_b32 v[186:187], v10 offset0:148 offset1:181
	ds_read2_b32 v[188:189], v10 offset0:214 offset1:247
	ds_read2_b32 v[190:191], v10 offset0:24 offset1:57
	ds_read2_b32 v[192:193], v10 offset0:90 offset1:123
	ds_read2_b32 v[194:195], v10 offset0:156 offset1:189
	ds_read2_b32 v[198:199], v10 offset0:222 offset1:255
	s_addc_u32 s7, s11, s5
	s_ashr_i32 s9, s8, 31
	s_waitcnt lgkmcnt(12)
	v_cvt_pk_bf16_f32 v14, v166, v167
	s_lshl_b64 s[4:5], s[8:9], 1
	s_waitcnt lgkmcnt(12)
	v_cvt_pk_bf16_f32 v15, v168, v169
	v_add_u32_e32 v18, s10, v5
	s_add_u32 s4, s6, s4
	v_ashrrev_i32_e32 v19, 31, v18
	s_waitcnt lgkmcnt(12)
	v_cvt_pk_bf16_f32 v16, v170, v171
	s_addc_u32 s5, s7, s5
	v_lshl_add_u64 v[20:21], s[4:5], 0, v[2:3]
	s_waitcnt lgkmcnt(12)
	v_cvt_pk_bf16_f32 v17, v172, v173
	v_lshlrev_b64 v[8:9], 12, v[18:19]
	v_lshl_add_u64 v[8:9], v[20:21], 0, v[8:9]
	global_store_dwordx4 v[8:9], v[14:17], off
	s_nop 1
	v_add_u32_e32 v18, s10, v11
	v_ashrrev_i32_e32 v19, 31, v18
	s_waitcnt lgkmcnt(8)
	v_cvt_pk_bf16_f32 v14, v174, v175
	v_lshlrev_b64 v[18:19], 12, v[18:19]
	s_waitcnt lgkmcnt(8)
	v_cvt_pk_bf16_f32 v15, v176, v177
	v_lshl_add_u64 v[18:19], v[20:21], 0, v[18:19]
	s_waitcnt lgkmcnt(8)
	v_cvt_pk_bf16_f32 v16, v178, v179
	s_waitcnt lgkmcnt(8)
	v_cvt_pk_bf16_f32 v17, v180, v181
	global_store_dwordx4 v[18:19], v[14:17], off
	s_nop 1
	v_add_u32_e32 v18, s10, v12
	v_ashrrev_i32_e32 v19, 31, v18
	s_waitcnt lgkmcnt(4)
	v_cvt_pk_bf16_f32 v14, v182, v183
	v_lshlrev_b64 v[18:19], 12, v[18:19]
	s_waitcnt lgkmcnt(4)
	v_cvt_pk_bf16_f32 v15, v184, v185
	v_lshl_add_u64 v[18:19], v[20:21], 0, v[18:19]
	s_waitcnt lgkmcnt(4)
	v_cvt_pk_bf16_f32 v16, v186, v187
	s_waitcnt lgkmcnt(4)
	v_cvt_pk_bf16_f32 v17, v188, v189
	global_store_dwordx4 v[18:19], v[14:17], off
	s_nop 1
	v_add_u32_e32 v18, s10, v13
	v_ashrrev_i32_e32 v19, 31, v18
	s_waitcnt lgkmcnt(0)
	v_cvt_pk_bf16_f32 v14, v190, v191
	v_lshlrev_b64 v[18:19], 12, v[18:19]
	s_waitcnt lgkmcnt(0)
	v_cvt_pk_bf16_f32 v15, v192, v193
	v_lshl_add_u64 v[18:19], v[20:21], 0, v[18:19]
	s_waitcnt lgkmcnt(0)
	v_cvt_pk_bf16_f32 v16, v194, v195
	s_waitcnt lgkmcnt(0)
	v_cvt_pk_bf16_f32 v17, v198, v199
	global_store_dwordx4 v[18:19], v[14:17], off
	s_nop 1
	s_waitcnt lgkmcnt(0)
	s_add_i32 s3, s3, s14
	s_cmpk_lt_i32 s3, 0x7400
	s_cbranch_scc1 .LBB0_454

.LBB0_1151:
	s_ashr_i32 s13, s12, 31
	s_lshl_b64 s[12:13], s[12:13], 3
	s_add_u32 s14, s0, s12
	s_addc_u32 s15, s1, s13
	s_lshr_b32 s12, s29, 5
	v_cvt_f32_u32_e32 v8, s12
	s_load_dwordx2 s[40:41], s[14:15], 0x0
	s_sub_i32 s14, 0, s12
	s_abs_i32 s46, s36
	v_rcp_iflag_f32_e32 v8, v8
	s_ashr_i32 s45, s36, 31
	s_mov_b32 s13, 0
	s_mov_b32 s44, 1
	v_mul_f32_e32 v8, 0x4f7ffffe, v8
	v_cvt_u32_f32_e32 v8, v8
	s_nop 0
	v_readfirstlane_b32 s15, v8
	s_mul_i32 s14, s14, s15
	s_mul_hi_u32 s14, s15, s14
	s_add_i32 s15, s15, s14
	s_mul_hi_u32 s14, s46, s15
	s_mul_i32 s15, s14, s12
	s_sub_i32 s15, s46, s15
	s_add_i32 s47, s14, 1
	s_sub_i32 s46, s15, s12
	s_cmp_ge_u32 s15, s12
	s_cselect_b32 s14, s47, s14
	s_cselect_b32 s15, s46, s15
	s_add_i32 s46, s14, 1
	s_cmp_ge_u32 s15, s12
	s_cselect_b32 s14, s46, s14
	s_xor_b32 s14, s14, s45
	s_sub_i32 s14, s14, s45
	s_mul_i32 s12, s14, s12
	s_sub_i32 s15, s36, s12
	s_lshl_b32 s12, s14, 6
	s_lshl_b32 s14, s15, 5
	s_ashr_i32 s15, s14, 31
	s_lshl_b64 s[46:47], s[14:15], 2
	s_waitcnt lgkmcnt(0)
	s_add_u32 s40, s40, s46
	s_addc_u32 s41, s41, s47
	s_mul_i32 s70, s12, s29
	s_lshl_b32 s71, s29, 2
	s_lshl_b32 s70, s70, 2
	s_add_u32 s40, s40, s70
	s_addc_u32 s41, s41, 0
	v_mad_u32_u24 v210, v0, s71, v6
	v_mad_u32_u24 v211, v0, s25, v4
	s_lshl_b32 s71, s71, 1
	global_load_dword v166, v210, s[40:41] nt
	s_add_u32 s40, s40, s71
	s_addc_u32 s41, s41, 0
	global_load_dword v167, v210, s[40:41] nt
	s_add_u32 s40, s40, s71
	s_addc_u32 s41, s41, 0
	global_load_dword v168, v210, s[40:41] nt
	s_add_u32 s40, s40, s71
	s_addc_u32 s41, s41, 0
	global_load_dword v169, v210, s[40:41] nt
	s_add_u32 s40, s40, s71
	s_addc_u32 s41, s41, 0
	global_load_dword v170, v210, s[40:41] nt
	s_add_u32 s40, s40, s71
	s_addc_u32 s41, s41, 0
	global_load_dword v171, v210, s[40:41] nt
	s_add_u32 s40, s40, s71
	s_addc_u32 s41, s41, 0
	global_load_dword v172, v210, s[40:41] nt
	s_add_u32 s40, s40, s71
	s_addc_u32 s41, s41, 0
	global_load_dword v173, v210, s[40:41] nt
	s_add_u32 s40, s40, s71
	s_addc_u32 s41, s41, 0
	global_load_dword v174, v210, s[40:41] nt
	s_add_u32 s40, s40, s71
	s_addc_u32 s41, s41, 0
	global_load_dword v175, v210, s[40:41] nt
	s_add_u32 s40, s40, s71
	s_addc_u32 s41, s41, 0
	global_load_dword v176, v210, s[40:41] nt
	s_add_u32 s40, s40, s71
	s_addc_u32 s41, s41, 0
	global_load_dword v177, v210, s[40:41] nt
	s_add_u32 s40, s40, s71
	s_addc_u32 s41, s41, 0
	global_load_dword v178, v210, s[40:41] nt
	s_add_u32 s40, s40, s71
	s_addc_u32 s41, s41, 0
	global_load_dword v179, v210, s[40:41] nt
	s_add_u32 s40, s40, s71
	s_addc_u32 s41, s41, 0
	global_load_dword v180, v210, s[40:41] nt
	s_add_u32 s40, s40, s71
	s_addc_u32 s41, s41, 0
	global_load_dword v181, v210, s[40:41] nt
	s_add_u32 s40, s40, s71
	s_addc_u32 s41, s41, 0
	global_load_dword v182, v210, s[40:41] nt
	s_add_u32 s40, s40, s71
	s_addc_u32 s41, s41, 0
	global_load_dword v183, v210, s[40:41] nt
	s_add_u32 s40, s40, s71
	s_addc_u32 s41, s41, 0
	global_load_dword v184, v210, s[40:41] nt
	s_add_u32 s40, s40, s71
	s_addc_u32 s41, s41, 0
	global_load_dword v185, v210, s[40:41] nt
	s_add_u32 s40, s40, s71
	s_addc_u32 s41, s41, 0
	global_load_dword v186, v210, s[40:41] nt
	s_add_u32 s40, s40, s71
	s_addc_u32 s41, s41, 0
	global_load_dword v187, v210, s[40:41] nt
	s_add_u32 s40, s40, s71
	s_addc_u32 s41, s41, 0
	global_load_dword v188, v210, s[40:41] nt
	s_add_u32 s40, s40, s71
	s_addc_u32 s41, s41, 0
	global_load_dword v189, v210, s[40:41] nt
	s_add_u32 s40, s40, s71
	s_addc_u32 s41, s41, 0
	global_load_dword v190, v210, s[40:41] nt
	s_add_u32 s40, s40, s71
	s_addc_u32 s41, s41, 0
	global_load_dword v191, v210, s[40:41] nt
	s_add_u32 s40, s40, s71
	s_addc_u32 s41, s41, 0
	global_load_dword v192, v210, s[40:41] nt
	s_add_u32 s40, s40, s71
	s_addc_u32 s41, s41, 0
	global_load_dword v193, v210, s[40:41] nt
	s_add_u32 s40, s40, s71
	s_addc_u32 s41, s41, 0
	global_load_dword v194, v210, s[40:41] nt
	s_add_u32 s40, s40, s71
	s_addc_u32 s41, s41, 0
	global_load_dword v195, v210, s[40:41] nt
	s_add_u32 s40, s40, s71
	s_addc_u32 s41, s41, 0
	global_load_dword v198, v210, s[40:41] nt
	s_add_u32 s40, s40, s71
	s_addc_u32 s41, s41, 0
	global_load_dword v199, v210, s[40:41] nt
	s_waitcnt vmcnt(31)
	ds_write_b32 v211, v166
	s_waitcnt vmcnt(30)
	ds_write_b32 v211, v167 offset:264
	s_waitcnt vmcnt(29)
	ds_write_b32 v211, v168 offset:528
	s_waitcnt vmcnt(28)
	ds_write_b32 v211, v169 offset:792
	s_waitcnt vmcnt(27)
	ds_write_b32 v211, v170 offset:1056
	s_waitcnt vmcnt(26)
	ds_write_b32 v211, v171 offset:1320
	s_waitcnt vmcnt(25)
	ds_write_b32 v211, v172 offset:1584
	s_waitcnt vmcnt(24)
	ds_write_b32 v211, v173 offset:1848
	s_waitcnt vmcnt(23)
	ds_write_b32 v211, v174 offset:2112
	s_waitcnt vmcnt(22)
	ds_write_b32 v211, v175 offset:2376
	s_waitcnt vmcnt(21)
	ds_write_b32 v211, v176 offset:2640
	s_waitcnt vmcnt(20)
	ds_write_b32 v211, v177 offset:2904
	s_waitcnt vmcnt(19)
	ds_write_b32 v211, v178 offset:3168
	s_waitcnt vmcnt(18)
	ds_write_b32 v211, v179 offset:3432
	s_waitcnt vmcnt(17)
	ds_write_b32 v211, v180 offset:3696
	s_waitcnt vmcnt(16)
	ds_write_b32 v211, v181 offset:3960
	s_waitcnt vmcnt(15)
	ds_write_b32 v211, v182 offset:4224
	s_waitcnt vmcnt(14)
	ds_write_b32 v211, v183 offset:4488
	s_waitcnt vmcnt(13)
	ds_write_b32 v211, v184 offset:4752
	s_waitcnt vmcnt(12)
	ds_write_b32 v211, v185 offset:5016
	s_waitcnt vmcnt(11)
	ds_write_b32 v211, v186 offset:5280
	s_waitcnt vmcnt(10)
	ds_write_b32 v211, v187 offset:5544
	s_waitcnt vmcnt(9)
	ds_write_b32 v211, v188 offset:5808
	s_waitcnt vmcnt(8)
	ds_write_b32 v211, v189 offset:6072
	s_waitcnt vmcnt(7)
	ds_write_b32 v211, v190 offset:6336
	s_waitcnt vmcnt(6)
	ds_write_b32 v211, v191 offset:6600
	s_waitcnt vmcnt(5)
	ds_write_b32 v211, v192 offset:6864
	s_waitcnt vmcnt(4)
	ds_write_b32 v211, v193 offset:7128
	s_waitcnt vmcnt(3)
	ds_write_b32 v211, v194 offset:7392
	s_waitcnt vmcnt(2)
	ds_write_b32 v211, v195 offset:7656
	s_waitcnt vmcnt(1)
	ds_write_b32 v211, v198 offset:7920
	s_waitcnt vmcnt(0)
	ds_write_b32 v211, v199 offset:8184
	s_add_u32 s13, s34, s8
	s_waitcnt lgkmcnt(0)
	s_addc_u32 s15, s35, s9
	s_add_i32 s14, s14, s37
	s_lshl_b64 s[8:9], s[10:11], 1
	s_add_u32 s10, s13, s8
	ds_read2_b32 v[166:167], v10 offset1:33
	ds_read2_b32 v[168:169], v10 offset0:66 offset1:99
	ds_read2_b32 v[170:171], v10 offset0:132 offset1:165
	ds_read2_b32 v[172:173], v10 offset0:198 offset1:231
	ds_read2_b32 v[174:175], v10 offset0:8 offset1:41
	ds_read2_b32 v[176:177], v10 offset0:74 offset1:107
	ds_read2_b32 v[178:179], v10 offset0:140 offset1:173
	ds_read2_b32 v[180:181], v10 offset0:206 offset1:239
	ds_read2_b32 v[182:183], v10 offset0:16 offset1:49
	ds_read2_b32 v[184:185], v10 offset0:82 offset1:115
	ds_read2_b32 v[186:187], v10 offset0:148 offset1:181
	ds_read2_b32 v[188:189], v10 offset0:214 offset1:247
	ds_read2_b32 v[190:191], v10 offset0:24 offset1:57
	ds_read2_b32 v[192:193], v10 offset0:90 offset1:123
	ds_read2_b32 v[194:195], v10 offset0:156 offset1:189
	ds_read2_b32 v[198:199], v10 offset0:222 offset1:255
	s_addc_u32 s11, s15, s9
	s_ashr_i32 s13, s12, 31
	s_waitcnt lgkmcnt(12)
	v_cvt_pk_bf16_f32 v14, v166, v167
	s_lshl_b64 s[8:9], s[12:13], 1
	s_waitcnt lgkmcnt(12)
	v_cvt_pk_bf16_f32 v15, v168, v169
	v_add_u32_e32 v20, s14, v5
	s_add_u32 s8, s10, s8
	v_ashrrev_i32_e32 v21, 31, v20
	s_waitcnt lgkmcnt(12)
	v_cvt_pk_bf16_f32 v16, v170, v171
	s_addc_u32 s9, s11, s9
	v_lshl_add_u64 v[18:19], s[8:9], 0, v[2:3]
	s_waitcnt lgkmcnt(12)
	v_cvt_pk_bf16_f32 v17, v172, v173
	v_mul_lo_u32 v21, s6, v21
	v_mul_lo_u32 v22, s7, v20
	v_mad_u64_u32 v[8:9], s[8:9], s6, v20, 0
	v_add3_u32 v9, v9, v21, v22
	v_lshl_add_u64 v[8:9], v[8:9], 1, v[18:19]
	global_store_dwordx4 v[8:9], v[14:17], off
	s_nop 1
	s_add_i32 s3, s3, s19
	v_add_u32_e32 v17, s14, v11
	s_waitcnt lgkmcnt(8)
	v_cvt_pk_bf16_f32 v14, v174, v175
	v_ashrrev_i32_e32 v22, 31, v17
	s_waitcnt lgkmcnt(8)
	v_cvt_pk_bf16_f32 v15, v176, v177
	v_mul_lo_u32 v23, s7, v17
	v_mad_u64_u32 v[20:21], s[8:9], s6, v17, 0
	v_mul_lo_u32 v17, s6, v22
	s_waitcnt lgkmcnt(8)
	v_cvt_pk_bf16_f32 v16, v178, v179
	v_add3_u32 v21, v21, v17, v23
	s_waitcnt lgkmcnt(8)
	v_cvt_pk_bf16_f32 v17, v180, v181
	v_lshl_add_u64 v[8:9], v[20:21], 1, v[18:19]
	global_store_dwordx4 v[8:9], v[14:17], off
	s_nop 1
	s_cmp_lt_i32 s3, 0x9400
	v_add_u32_e32 v17, s14, v12
	v_ashrrev_i32_e32 v22, 31, v17
	v_mul_lo_u32 v23, s7, v17
	v_mad_u64_u32 v[20:21], s[8:9], s6, v17, 0
	v_mul_lo_u32 v17, s6, v22
	s_waitcnt lgkmcnt(4)
	v_cvt_pk_bf16_f32 v14, v182, v183
	v_add3_u32 v21, v21, v17, v23
	s_waitcnt lgkmcnt(4)
	v_cvt_pk_bf16_f32 v15, v184, v185
	s_waitcnt lgkmcnt(4)
	v_cvt_pk_bf16_f32 v16, v186, v187
	v_lshl_add_u64 v[20:21], v[20:21], 1, v[18:19]
	s_waitcnt lgkmcnt(4)
	v_cvt_pk_bf16_f32 v17, v188, v189
	global_store_dwordx4 v[20:21], v[14:17], off
	s_nop 1
	s_nop 0
	v_add_u32_e32 v16, s14, v13
	v_ashrrev_i32_e32 v17, 31, v16
	v_mul_lo_u32 v22, s7, v16
	v_mad_u64_u32 v[20:21], s[8:9], s6, v16, 0
	v_mul_lo_u32 v17, s6, v17
	s_waitcnt lgkmcnt(0)
	v_cvt_pk_bf16_f32 v14, v190, v191
	v_add3_u32 v21, v21, v17, v22
	s_waitcnt lgkmcnt(0)
	v_cvt_pk_bf16_f32 v15, v192, v193
	v_lshl_add_u64 v[18:19], v[20:21], 1, v[18:19]
	s_waitcnt lgkmcnt(0)
	v_cvt_pk_bf16_f32 v16, v194, v195
	s_waitcnt lgkmcnt(0)
	v_cvt_pk_bf16_f32 v17, v198, v199
	global_store_dwordx4 v[18:19], v[14:17], off
	s_nop 1
	s_waitcnt lgkmcnt(0)
	s_cbranch_scc1 .LBB0_1111
